# P1 epilogue stores written through (sc0 sc1) so the barrier's L2 writeback behind P1 has little left to flush
# baseline (speedup 1.0000x reference)
; #define LAS __attribute__((address_space(3)))
; __device__ __forceinline__ float sigmoidf_(float x) { return __builtin_amdgcn_rcpf(1.f + __builtin_amdgcn_exp2f(-1.4426950408889634f * x)); }
; #define EPI_FOR_ROWS for (int ai = 0; ai < 2; ++ai) _Pragma("unroll") for (int m = 0; m < 4; ++m)
; __device__ __forceinline__ u32x4 pack8(const f32x4 a, const f32x4 b) { u32x4 w; w.x = cvt_pk_bf16(a[0], a[1]); w.y = cvt_pk_bf16(a[2], a[3]); w.z = cvt_pk_bf16(b[0], b[1]); w.w = cvt_pk_bf16(b[2], b[3]); return w; }
;     __device__ __forceinline__ void conv_piece(size_t row, int ch, f32x4 v0, f32x4 v1, const f32x4 g0, const f32x4 g1) const {
; #pragma unroll
;         for (int e = 0; e < 4; ++e) { v0[e] *= sigmoidf_(g0[e]); v1[e] *= sigmoidf_(g1[e]); }
;         *(u32x4*)(Vb + row * DCONV + ch) = pack8(v0, v1);
;         float* dst = nullptr;
;         if (row >= (size_t)NP) { const int r = (int)row - NP; dst = out + O_CVS + (size_t)((r >> 4) * 30 + 14 + (r & 15)) * DCONV + ch; }
;         else { const int t = (int)row & (SEQ - 1); if (t >= SEQ - 30) dst = out + O_CVP + (size_t)(((int)row >> 14) * 30 + (t - (SEQ - 30))) * DCONV + ch; }
;         if (dst) { *(f32x4*)dst = v0; *(f32x4*)(dst + 4) = v1; }
;     }
;     __device__ __forceinline__ void small(size_t row, int col, const f32x4 v0, const f32x4 v1) const { *(u32x4*)(Ub + row * DSSM + col) = pack8(v0, v1); }
;     __device__ __forceinline__ void operator()(const f32x4 (&acc)[2][2][4][2], const Unit& u, int wr, int wc, int fr_, int fq_, LAS unsigned char*) const {
;         int fr = fr_, fq = fq_; asm volatile("" : "+v"(fr), "+v"(fq));
;         const int pn = u.aux;
; #pragma unroll
;         EPI_FOR_ROWS {
;             const int rl = ai * HALF + wr * 64 + m * 16 + fr; const size_t row = (size_t)u.row0 + rl;
;             if (pn < 2) {
; #pragma unroll
;                 for (int bj = 0; bj < 2; ++bj) *(u32x4*)(Ub + row * DSSM + pn * 256 + bj * HALF + wc * 32 + 8 * fq) = pack8(acc[ai][bj][m][0], acc[ai][bj][m][1]);
;             } else {
;                 conv_piece(row, (pn - 2) * 128 + wc * 32 + 8 * fq, acc[ai][0][m][0], acc[ai][0][m][1], acc[ai][1][m][0], acc[ai][1][m][1]);
.LBB0_331:
	s_ashr_i32 s17, s16, 31
	v_mov_b32_e32 v128, v166
	v_mov_b32_e32 v129, v167
	s_cmp_gt_i32 s10, 1
	s_cselect_b64 s[28:29], -1, 0
	v_add_u32_e32 v158, s70, v128
	s_lshl_b32 s4, s10, 7
	v_lshlrev_b32_e32 v154, 3, v129
	s_add_i32 s4, s75, s4
	v_ashrrev_i32_e32 v159, 31, v158
	v_add_u32_e32 v156, s4, v154
	v_lshl_add_u64 v[162:163], v[158:159], 0, s[16:17]
	v_ashrrev_i32_e32 v157, 31, v156
	s_mov_b64 s[4:5], -1
	s_and_b64 vcc, exec, s[28:29]
	v_lshlrev_b64 v[160:161], 10, v[162:163]
	s_cbranch_vccz .LBB0_339
	v_mul_f32_e32 v129, 0xbfb8aa3b, v112
	v_mul_f32_e32 v130, 0xbfb8aa3b, v117
	v_exp_f32_e32 v129, v129
	v_exp_f32_e32 v131, v130
	v_mul_f32_e32 v130, 0xbfb8aa3b, v113
	v_exp_f32_e32 v132, v130
	v_add_f32_e32 v129, 1.0, v129
	v_rcp_f32_e32 v130, v129
	v_add_f32_e32 v129, 1.0, v131
	v_add_f32_e32 v131, 1.0, v132
	v_mul_f32_e32 v132, 0xbfb8aa3b, v118
	v_exp_f32_e32 v132, v132
	v_mul_f32_e32 v133, 0xbfb8aa3b, v114
	v_exp_f32_e32 v133, v133
	v_mul_f32_e32 v128, 0xbfb8aa3b, v116
	v_add_f32_e32 v132, 1.0, v132
	v_rcp_f32_e32 v134, v132
	v_add_f32_e32 v132, 1.0, v133
	v_mul_f32_e32 v133, 0xbfb8aa3b, v119
	v_exp_f32_e32 v133, v133
	v_mul_f32_e32 v135, 0xbfb8aa3b, v115
	v_exp_f32_e32 v128, v128
	v_exp_f32_e32 v144, v135
	v_rcp_f32_e32 v164, v132
	v_add_f32_e32 v132, 1.0, v133
	v_add_f32_e32 v128, 1.0, v128
	v_rcp_f32_e32 v135, v132
	v_add_f32_e32 v132, 1.0, v144
	v_rcp_f32_e32 v128, v128
	v_rcp_f32_e32 v129, v129
	v_rcp_f32_e32 v131, v131
	v_rcp_f32_e32 v165, v132
	v_pk_mul_f32 v[134:135], v[126:127], v[134:135]
	v_pk_mul_f32 v[132:133], v[124:125], v[128:129]
	v_pk_mul_f32 v[128:129], v[120:121], v[130:131]
	v_pk_mul_f32 v[130:131], v[122:123], v[164:165]
	v_lshl_add_u64 v[164:165], s[36:37], 0, v[160:161]
	v_lshl_add_u64 v[164:165], v[156:157], 1, v[164:165]
	v_cmp_gt_u64_e32 vcc, s[20:21], v[162:163]
	v_cvt_pk_bf16_f32 v172, v132, v133
	v_cvt_pk_bf16_f32 v173, v134, v135
	v_cvt_pk_bf16_f32 v174, v128, v129
	v_cvt_pk_bf16_f32 v175, v130, v131
	global_store_dwordx4 v[164:165], v[172:175], off sc0 sc1
	s_and_saveexec_b64 s[4:5], vcc
	s_xor_b64 s[4:5], exec, s[4:5]
	s_cbranch_execz .LBB0_414
	v_and_b32_e32 v144, 0x3fff, v162
	v_cmp_lt_u32_e32 vcc, s78, v144
	v_mov_b64_e32 v[164:165], 0
	s_and_saveexec_b64 s[26:27], vcc
	v_lshrrev_b32_e32 v155, 14, v162
	v_mul_u32_u24_e32 v155, 30, v155
	v_add3_u32 v144, v144, v155, s79
	v_lshlrev_b64 v[162:163], 11, v[144:145]
	v_lshl_add_u64 v[162:163], s[6:7], 0, v[162:163]
	v_lshl_add_u64 v[164:165], v[156:157], 2, v[162:163]
	s_or_b64 exec, exec, s[26:27]
	s_andn2_saveexec_b64 s[4:5], s[4:5]
	s_cbranch_execnz .LBB0_415

;     __device__ __forceinline__ void conv_piece(size_t row, int ch, f32x4 v0, f32x4 v1, const f32x4 g0, const f32x4 g1) const {
;     ...
;         if (row >= (size_t)NP) { const int r = (int)row - NP; dst = out + O_CVS + (size_t)((r >> 4) * 30 + 14 + (r & 15)) * DCONV + ch; }
;         else { const int t = (int)row & (SEQ - 1); if (t >= SEQ - 30) dst = out + O_CVP + (size_t)(((int)row >> 14) * 30 + (t - (SEQ - 30))) * DCONV + ch; }
;         if (dst) { *(f32x4*)dst = v0; *(f32x4*)(dst + 4) = v1; }
.LBB0_337:
	global_store_dwordx4 v[164:165], v[132:135], off sc0 sc1
	global_store_dwordx4 v[164:165], v[128:131], off offset:16 sc0 sc1

; #define LAS __attribute__((address_space(3)))
; __device__ __forceinline__ float sigmoidf_(float x) { return __builtin_amdgcn_rcpf(1.f + __builtin_amdgcn_exp2f(-1.4426950408889634f * x)); }
; #define EPI_FOR_ROWS for (int ai = 0; ai < 2; ++ai) _Pragma("unroll") for (int m = 0; m < 4; ++m)
; __device__ __forceinline__ u32x4 pack8(const f32x4 a, const f32x4 b) { u32x4 w; w.x = cvt_pk_bf16(a[0], a[1]); w.y = cvt_pk_bf16(a[2], a[3]); w.z = cvt_pk_bf16(b[0], b[1]); w.w = cvt_pk_bf16(b[2], b[3]); return w; }
;     __device__ __forceinline__ void conv_piece(size_t row, int ch, f32x4 v0, f32x4 v1, const f32x4 g0, const f32x4 g1) const {
; #pragma unroll
;         for (int e = 0; e < 4; ++e) { v0[e] *= sigmoidf_(g0[e]); v1[e] *= sigmoidf_(g1[e]); }
;         *(u32x4*)(Vb + row * DCONV + ch) = pack8(v0, v1);
;         float* dst = nullptr;
;         if (row >= (size_t)NP) { const int r = (int)row - NP; dst = out + O_CVS + (size_t)((r >> 4) * 30 + 14 + (r & 15)) * DCONV + ch; }
;         else { const int t = (int)row & (SEQ - 1); if (t >= SEQ - 30) dst = out + O_CVP + (size_t)(((int)row >> 14) * 30 + (t - (SEQ - 30))) * DCONV + ch; }
;         if (dst) { *(f32x4*)dst = v0; *(f32x4*)(dst + 4) = v1; }
;     }
;     __device__ __forceinline__ void small(size_t row, int col, const f32x4 v0, const f32x4 v1) const { *(u32x4*)(Ub + row * DSSM + col) = pack8(v0, v1); }
;     __device__ __forceinline__ void operator()(const f32x4 (&acc)[2][2][4][2], const Unit& u, int wr, int wc, int fr_, int fq_, LAS unsigned char*) const {
;         int fr = fr_, fq = fq_; asm volatile("" : "+v"(fr), "+v"(fq));
;         const int pn = u.aux;
; #pragma unroll
;         EPI_FOR_ROWS {
;             const int rl = ai * HALF + wr * 64 + m * 16 + fr; const size_t row = (size_t)u.row0 + rl;
;             if (pn < 2) {
; #pragma unroll
;                 for (int bj = 0; bj < 2; ++bj) *(u32x4*)(Ub + row * DSSM + pn * 256 + bj * HALF + wc * 32 + 8 * fq) = pack8(acc[ai][bj][m][0], acc[ai][bj][m][1]);
;             } else {
;                 conv_piece(row, (pn - 2) * 128 + wc * 32 + 8 * fq, acc[ai][0][m][0], acc[ai][0][m][1], acc[ai][1][m][0], acc[ai][1][m][1]);
.LBB0_339:
	s_lshl_b32 s62, s10, 8
	s_ashr_i32 s63, s62, 31
	v_ashrrev_i32_e32 v155, 31, v154
	s_and_b64 vcc, exec, s[4:5]
	s_cbranch_vccz .LBB0_341
	v_cvt_pk_bf16_f32 v124, v124, v125
	v_cvt_pk_bf16_f32 v125, v126, v127
	v_cvt_pk_bf16_f32 v126, v120, v121
	v_lshl_add_u64 v[120:121], s[60:61], 0, v[160:161]
	v_lshl_add_u64 v[120:121], s[62:63], 1, v[120:121]
	s_lshl_b32 s10, s71, 1
	v_lshl_add_u64 v[120:121], v[120:121], 0, s[10:11]
	v_lshl_add_u64 v[120:121], v[154:155], 1, v[120:121]
	v_cvt_pk_bf16_f32 v127, v122, v123
	global_store_dwordx4 v[120:121], v[124:127], off sc0 sc1
	v_cvt_pk_bf16_f32 v116, v116, v117
	v_cvt_pk_bf16_f32 v117, v118, v119
	v_cvt_pk_bf16_f32 v118, v112, v113
	v_cvt_pk_bf16_f32 v119, v114, v115
	global_store_dwordx4 v[120:121], v[116:119], off offset:256 sc0 sc1
.LBB0_341:
	v_add_u32_e32 v112, 16, v158
	v_ashrrev_i32_e32 v113, 31, v112
	v_lshl_add_u64 v[122:123], v[112:113], 0, s[16:17]
	v_cndmask_b32_e64 v112, 0, 1, s[28:29]
	s_mov_b64 s[26:27], -1
	v_cmp_ne_u32_e64 s[4:5], 1, v112
	s_andn2_b64 vcc, exec, s[28:29]
	v_lshlrev_b64 v[120:121], 10, v[122:123]
	s_cbranch_vccnz .LBB0_349
	v_mul_f32_e32 v113, 0xbfb8aa3b, v96
	v_mul_f32_e32 v114, 0xbfb8aa3b, v101
	v_exp_f32_e32 v113, v113
	v_exp_f32_e32 v115, v114
	v_mul_f32_e32 v114, 0xbfb8aa3b, v97
	v_exp_f32_e32 v116, v114
	v_add_f32_e32 v113, 1.0, v113
	v_rcp_f32_e32 v114, v113
	v_add_f32_e32 v113, 1.0, v115
	v_add_f32_e32 v115, 1.0, v116
	v_mul_f32_e32 v116, 0xbfb8aa3b, v102
	v_exp_f32_e32 v116, v116
	v_mul_f32_e32 v117, 0xbfb8aa3b, v98
	v_exp_f32_e32 v117, v117
	v_mul_f32_e32 v112, 0xbfb8aa3b, v100
	v_add_f32_e32 v116, 1.0, v116
	v_rcp_f32_e32 v118, v116
	v_add_f32_e32 v116, 1.0, v117
	v_mul_f32_e32 v117, 0xbfb8aa3b, v103
	v_exp_f32_e32 v117, v117
	v_mul_f32_e32 v119, 0xbfb8aa3b, v99
	v_exp_f32_e32 v112, v112
	v_exp_f32_e32 v125, v119
	v_rcp_f32_e32 v124, v116
	v_add_f32_e32 v116, 1.0, v117
	v_add_f32_e32 v112, 1.0, v112
	v_rcp_f32_e32 v119, v116
	v_add_f32_e32 v116, 1.0, v125
	v_rcp_f32_e32 v112, v112
	v_rcp_f32_e32 v113, v113
	v_rcp_f32_e32 v115, v115
	v_rcp_f32_e32 v125, v116
	v_lshl_add_u64 v[128:129], s[36:37], 0, v[120:121]
	v_pk_mul_f32 v[116:117], v[108:109], v[112:113]
	v_pk_mul_f32 v[112:113], v[104:105], v[114:115]
	v_pk_mul_f32 v[118:119], v[110:111], v[118:119]
	v_pk_mul_f32 v[114:115], v[106:107], v[124:125]
	v_cvt_pk_bf16_f32 v124, v116, v117
	v_cvt_pk_bf16_f32 v125, v118, v119
	v_lshl_add_u64 v[128:129], v[156:157], 1, v[128:129]
	v_cmp_gt_u64_e32 vcc, s[20:21], v[122:123]
	v_cvt_pk_bf16_f32 v126, v112, v113
	v_cvt_pk_bf16_f32 v127, v114, v115
	global_store_dwordx4 v[128:129], v[124:127], off sc0 sc1
	s_and_saveexec_b64 s[26:27], vcc
	s_xor_b64 s[26:27], exec, s[26:27]
	s_cbranch_execz .LBB0_416
	v_and_b32_e32 v123, 0x3fff, v122
	v_cmp_lt_u32_e32 vcc, s78, v123
	v_mov_b64_e32 v[124:125], 0
	s_and_saveexec_b64 s[28:29], vcc
	v_lshrrev_b32_e32 v122, 14, v122
	v_mul_u32_u24_e32 v122, 30, v122
	v_add3_u32 v144, v123, v122, s79
	v_lshlrev_b64 v[122:123], 11, v[144:145]
	v_lshl_add_u64 v[122:123], s[6:7], 0, v[122:123]
	v_lshl_add_u64 v[124:125], v[156:157], 2, v[122:123]
	s_or_b64 exec, exec, s[28:29]
	s_andn2_saveexec_b64 s[26:27], s[26:27]
	s_cbranch_execnz .LBB0_417

;     __device__ __forceinline__ void conv_piece(size_t row, int ch, f32x4 v0, f32x4 v1, const f32x4 g0, const f32x4 g1) const {
;     ...
;         if (row >= (size_t)NP) { const int r = (int)row - NP; dst = out + O_CVS + (size_t)((r >> 4) * 30 + 14 + (r & 15)) * DCONV + ch; }
;         else { const int t = (int)row & (SEQ - 1); if (t >= SEQ - 30) dst = out + O_CVP + (size_t)(((int)row >> 14) * 30 + (t - (SEQ - 30))) * DCONV + ch; }
;         if (dst) { *(f32x4*)dst = v0; *(f32x4*)(dst + 4) = v1; }
.LBB0_347:
	global_store_dwordx4 v[124:125], v[116:119], off sc0 sc1
	global_store_dwordx4 v[124:125], v[112:115], off offset:16 sc0 sc1

; #define LAS __attribute__((address_space(3)))
; __device__ __forceinline__ float sigmoidf_(float x) { return __builtin_amdgcn_rcpf(1.f + __builtin_amdgcn_exp2f(-1.4426950408889634f * x)); }
; #define EPI_FOR_ROWS for (int ai = 0; ai < 2; ++ai) _Pragma("unroll") for (int m = 0; m < 4; ++m)
; __device__ __forceinline__ u32x4 pack8(const f32x4 a, const f32x4 b) { u32x4 w; w.x = cvt_pk_bf16(a[0], a[1]); w.y = cvt_pk_bf16(a[2], a[3]); w.z = cvt_pk_bf16(b[0], b[1]); w.w = cvt_pk_bf16(b[2], b[3]); return w; }
;     __device__ __forceinline__ void conv_piece(size_t row, int ch, f32x4 v0, f32x4 v1, const f32x4 g0, const f32x4 g1) const {
; #pragma unroll
;         for (int e = 0; e < 4; ++e) { v0[e] *= sigmoidf_(g0[e]); v1[e] *= sigmoidf_(g1[e]); }
;         *(u32x4*)(Vb + row * DCONV + ch) = pack8(v0, v1);
;         float* dst = nullptr;
;         if (row >= (size_t)NP) { const int r = (int)row - NP; dst = out + O_CVS + (size_t)((r >> 4) * 30 + 14 + (r & 15)) * DCONV + ch; }
;         else { const int t = (int)row & (SEQ - 1); if (t >= SEQ - 30) dst = out + O_CVP + (size_t)(((int)row >> 14) * 30 + (t - (SEQ - 30))) * DCONV + ch; }
;         if (dst) { *(f32x4*)dst = v0; *(f32x4*)(dst + 4) = v1; }
;     }
;     __device__ __forceinline__ void small(size_t row, int col, const f32x4 v0, const f32x4 v1) const { *(u32x4*)(Ub + row * DSSM + col) = pack8(v0, v1); }
;     __device__ __forceinline__ void operator()(const f32x4 (&acc)[2][2][4][2], const Unit& u, int wr, int wc, int fr_, int fq_, LAS unsigned char*) const {
;         int fr = fr_, fq = fq_; asm volatile("" : "+v"(fr), "+v"(fq));
;         const int pn = u.aux;
; #pragma unroll
;         EPI_FOR_ROWS {
;             const int rl = ai * HALF + wr * 64 + m * 16 + fr; const size_t row = (size_t)u.row0 + rl;
;             if (pn < 2) {
; #pragma unroll
;                 for (int bj = 0; bj < 2; ++bj) *(u32x4*)(Ub + row * DSSM + pn * 256 + bj * HALF + wc * 32 + 8 * fq) = pack8(acc[ai][bj][m][0], acc[ai][bj][m][1]);
;             } else {
;                 conv_piece(row, (pn - 2) * 128 + wc * 32 + 8 * fq, acc[ai][0][m][0], acc[ai][0][m][1], acc[ai][1][m][0], acc[ai][1][m][1]);
.LBB0_349:
	s_and_b64 vcc, exec, s[26:27]
	s_cbranch_vccz .LBB0_351
	v_cvt_pk_bf16_f32 v108, v108, v109
	v_cvt_pk_bf16_f32 v109, v110, v111
	v_cvt_pk_bf16_f32 v110, v104, v105
	v_lshl_add_u64 v[104:105], s[60:61], 0, v[120:121]
	v_lshl_add_u64 v[104:105], s[62:63], 1, v[104:105]
	s_lshl_b32 s10, s71, 1
	v_lshl_add_u64 v[104:105], v[104:105], 0, s[10:11]
	v_lshl_add_u64 v[104:105], v[154:155], 1, v[104:105]
	v_cvt_pk_bf16_f32 v111, v106, v107
	global_store_dwordx4 v[104:105], v[108:111], off sc0 sc1
	v_cvt_pk_bf16_f32 v100, v100, v101
	v_cvt_pk_bf16_f32 v101, v102, v103
	v_cvt_pk_bf16_f32 v102, v96, v97
	v_cvt_pk_bf16_f32 v103, v98, v99
	global_store_dwordx4 v[104:105], v[100:103], off offset:256 sc0 sc1
.LBB0_351:
	v_add_u32_e32 v96, 32, v158
	v_ashrrev_i32_e32 v97, 31, v96
	v_lshl_add_u64 v[106:107], v[96:97], 0, s[16:17]
	s_mov_b64 s[26:27], -1
	s_and_b64 vcc, exec, s[4:5]
	v_lshlrev_b64 v[104:105], 10, v[106:107]
	s_cbranch_vccnz .LBB0_359
	v_mul_f32_e32 v97, 0xbfb8aa3b, v80
	v_mul_f32_e32 v98, 0xbfb8aa3b, v85
	v_exp_f32_e32 v97, v97
	v_exp_f32_e32 v99, v98
	v_mul_f32_e32 v98, 0xbfb8aa3b, v81
	v_exp_f32_e32 v100, v98
	v_add_f32_e32 v97, 1.0, v97
	v_rcp_f32_e32 v98, v97
	v_add_f32_e32 v97, 1.0, v99
	v_add_f32_e32 v99, 1.0, v100
	v_mul_f32_e32 v100, 0xbfb8aa3b, v86
	v_exp_f32_e32 v100, v100
	v_mul_f32_e32 v101, 0xbfb8aa3b, v82
	v_exp_f32_e32 v101, v101
	v_mul_f32_e32 v96, 0xbfb8aa3b, v84
	v_add_f32_e32 v100, 1.0, v100
	v_rcp_f32_e32 v102, v100
	v_add_f32_e32 v100, 1.0, v101
	v_mul_f32_e32 v101, 0xbfb8aa3b, v87
	v_exp_f32_e32 v101, v101
	v_mul_f32_e32 v103, 0xbfb8aa3b, v83
	v_exp_f32_e32 v96, v96
	v_exp_f32_e32 v109, v103
	v_rcp_f32_e32 v108, v100
	v_add_f32_e32 v100, 1.0, v101
	v_add_f32_e32 v96, 1.0, v96
	v_rcp_f32_e32 v103, v100
	v_add_f32_e32 v100, 1.0, v109
	v_rcp_f32_e32 v96, v96
	v_rcp_f32_e32 v97, v97
	v_rcp_f32_e32 v99, v99
	v_rcp_f32_e32 v109, v100
	v_lshl_add_u64 v[112:113], s[36:37], 0, v[104:105]
	v_pk_mul_f32 v[100:101], v[92:93], v[96:97]
	v_pk_mul_f32 v[96:97], v[88:89], v[98:99]
	v_pk_mul_f32 v[102:103], v[94:95], v[102:103]
	v_pk_mul_f32 v[98:99], v[90:91], v[108:109]
	v_cvt_pk_bf16_f32 v108, v100, v101
	v_cvt_pk_bf16_f32 v109, v102, v103
	v_lshl_add_u64 v[112:113], v[156:157], 1, v[112:113]
	v_cmp_gt_u64_e32 vcc, s[20:21], v[106:107]
	v_cvt_pk_bf16_f32 v110, v96, v97
	v_cvt_pk_bf16_f32 v111, v98, v99
	global_store_dwordx4 v[112:113], v[108:111], off sc0 sc1
	s_and_saveexec_b64 s[26:27], vcc
	s_xor_b64 s[26:27], exec, s[26:27]
	s_cbranch_execz .LBB0_418
	v_and_b32_e32 v107, 0x3fff, v106
	v_cmp_lt_u32_e32 vcc, s78, v107
	v_mov_b64_e32 v[108:109], 0
	s_and_saveexec_b64 s[28:29], vcc
	v_lshrrev_b32_e32 v106, 14, v106
	v_mul_u32_u24_e32 v106, 30, v106
	v_add3_u32 v144, v107, v106, s79
	v_lshlrev_b64 v[106:107], 11, v[144:145]
	v_lshl_add_u64 v[106:107], s[6:7], 0, v[106:107]
	v_lshl_add_u64 v[108:109], v[156:157], 2, v[106:107]
	s_or_b64 exec, exec, s[28:29]
	s_andn2_saveexec_b64 s[26:27], s[26:27]
	s_cbranch_execnz .LBB0_419

;     __device__ __forceinline__ void conv_piece(size_t row, int ch, f32x4 v0, f32x4 v1, const f32x4 g0, const f32x4 g1) const {
;     ...
;         if (row >= (size_t)NP) { const int r = (int)row - NP; dst = out + O_CVS + (size_t)((r >> 4) * 30 + 14 + (r & 15)) * DCONV + ch; }
;         else { const int t = (int)row & (SEQ - 1); if (t >= SEQ - 30) dst = out + O_CVP + (size_t)(((int)row >> 14) * 30 + (t - (SEQ - 30))) * DCONV + ch; }
;         if (dst) { *(f32x4*)dst = v0; *(f32x4*)(dst + 4) = v1; }
.LBB0_357:
	global_store_dwordx4 v[108:109], v[100:103], off sc0 sc1
	global_store_dwordx4 v[108:109], v[96:99], off offset:16 sc0 sc1

; #define LAS __attribute__((address_space(3)))
; __device__ __forceinline__ float sigmoidf_(float x) { return __builtin_amdgcn_rcpf(1.f + __builtin_amdgcn_exp2f(-1.4426950408889634f * x)); }
; #define EPI_FOR_ROWS for (int ai = 0; ai < 2; ++ai) _Pragma("unroll") for (int m = 0; m < 4; ++m)
; __device__ __forceinline__ u32x4 pack8(const f32x4 a, const f32x4 b) { u32x4 w; w.x = cvt_pk_bf16(a[0], a[1]); w.y = cvt_pk_bf16(a[2], a[3]); w.z = cvt_pk_bf16(b[0], b[1]); w.w = cvt_pk_bf16(b[2], b[3]); return w; }
;     __device__ __forceinline__ void conv_piece(size_t row, int ch, f32x4 v0, f32x4 v1, const f32x4 g0, const f32x4 g1) const {
; #pragma unroll
;         for (int e = 0; e < 4; ++e) { v0[e] *= sigmoidf_(g0[e]); v1[e] *= sigmoidf_(g1[e]); }
;         *(u32x4*)(Vb + row * DCONV + ch) = pack8(v0, v1);
;         float* dst = nullptr;
;         if (row >= (size_t)NP) { const int r = (int)row - NP; dst = out + O_CVS + (size_t)((r >> 4) * 30 + 14 + (r & 15)) * DCONV + ch; }
;         else { const int t = (int)row & (SEQ - 1); if (t >= SEQ - 30) dst = out + O_CVP + (size_t)(((int)row >> 14) * 30 + (t - (SEQ - 30))) * DCONV + ch; }
;         if (dst) { *(f32x4*)dst = v0; *(f32x4*)(dst + 4) = v1; }
;     }
;     __device__ __forceinline__ void small(size_t row, int col, const f32x4 v0, const f32x4 v1) const { *(u32x4*)(Ub + row * DSSM + col) = pack8(v0, v1); }
;     __device__ __forceinline__ void operator()(const f32x4 (&acc)[2][2][4][2], const Unit& u, int wr, int wc, int fr_, int fq_, LAS unsigned char*) const {
;         int fr = fr_, fq = fq_; asm volatile("" : "+v"(fr), "+v"(fq));
;         const int pn = u.aux;
; #pragma unroll
;         EPI_FOR_ROWS {
;             const int rl = ai * HALF + wr * 64 + m * 16 + fr; const size_t row = (size_t)u.row0 + rl;
;             if (pn < 2) {
; #pragma unroll
;                 for (int bj = 0; bj < 2; ++bj) *(u32x4*)(Ub + row * DSSM + pn * 256 + bj * HALF + wc * 32 + 8 * fq) = pack8(acc[ai][bj][m][0], acc[ai][bj][m][1]);
;             } else {
;                 conv_piece(row, (pn - 2) * 128 + wc * 32 + 8 * fq, acc[ai][0][m][0], acc[ai][0][m][1], acc[ai][1][m][0], acc[ai][1][m][1]);
.LBB0_359:
	s_and_b64 vcc, exec, s[26:27]
	s_cbranch_vccz .LBB0_361
	v_cvt_pk_bf16_f32 v92, v92, v93
	v_cvt_pk_bf16_f32 v93, v94, v95
	v_cvt_pk_bf16_f32 v94, v88, v89
	v_lshl_add_u64 v[88:89], s[60:61], 0, v[104:105]
	v_lshl_add_u64 v[88:89], s[62:63], 1, v[88:89]
	s_lshl_b32 s10, s71, 1
	v_lshl_add_u64 v[88:89], v[88:89], 0, s[10:11]
	v_lshl_add_u64 v[88:89], v[154:155], 1, v[88:89]
	v_cvt_pk_bf16_f32 v95, v90, v91
	global_store_dwordx4 v[88:89], v[92:95], off sc0 sc1
	v_cvt_pk_bf16_f32 v84, v84, v85
	v_cvt_pk_bf16_f32 v85, v86, v87
	v_cvt_pk_bf16_f32 v86, v80, v81
	v_cvt_pk_bf16_f32 v87, v82, v83
	global_store_dwordx4 v[88:89], v[84:87], off offset:256 sc0 sc1
.LBB0_361:
	v_add_u32_e32 v80, 48, v158
	v_ashrrev_i32_e32 v81, 31, v80
	v_lshl_add_u64 v[90:91], v[80:81], 0, s[16:17]
	s_mov_b64 s[26:27], -1
	s_and_b64 vcc, exec, s[4:5]
	v_lshlrev_b64 v[88:89], 10, v[90:91]
	s_cbranch_vccnz .LBB0_369
	v_mul_f32_e32 v81, 0xbfb8aa3b, v64
	v_mul_f32_e32 v82, 0xbfb8aa3b, v69
	v_exp_f32_e32 v81, v81
	v_exp_f32_e32 v83, v82
	v_mul_f32_e32 v82, 0xbfb8aa3b, v65
	v_exp_f32_e32 v84, v82
	v_add_f32_e32 v81, 1.0, v81
	v_rcp_f32_e32 v82, v81
	v_add_f32_e32 v81, 1.0, v83
	v_add_f32_e32 v83, 1.0, v84
	v_mul_f32_e32 v84, 0xbfb8aa3b, v70
	v_exp_f32_e32 v84, v84
	v_mul_f32_e32 v85, 0xbfb8aa3b, v66
	v_exp_f32_e32 v85, v85
	v_mul_f32_e32 v80, 0xbfb8aa3b, v68
	v_add_f32_e32 v84, 1.0, v84
	v_rcp_f32_e32 v86, v84
	v_add_f32_e32 v84, 1.0, v85
	v_mul_f32_e32 v85, 0xbfb8aa3b, v71
	v_exp_f32_e32 v85, v85
	v_mul_f32_e32 v87, 0xbfb8aa3b, v67
	v_exp_f32_e32 v80, v80
	v_exp_f32_e32 v93, v87
	v_rcp_f32_e32 v92, v84
	v_add_f32_e32 v84, 1.0, v85
	v_add_f32_e32 v80, 1.0, v80
	v_rcp_f32_e32 v87, v84
	v_add_f32_e32 v84, 1.0, v93
	v_rcp_f32_e32 v80, v80
	v_rcp_f32_e32 v81, v81
	v_rcp_f32_e32 v83, v83
	v_rcp_f32_e32 v93, v84
	v_lshl_add_u64 v[96:97], s[36:37], 0, v[88:89]
	v_pk_mul_f32 v[84:85], v[76:77], v[80:81]
	v_pk_mul_f32 v[80:81], v[72:73], v[82:83]
	v_pk_mul_f32 v[86:87], v[78:79], v[86:87]
	v_pk_mul_f32 v[82:83], v[74:75], v[92:93]
	v_cvt_pk_bf16_f32 v92, v84, v85
	v_cvt_pk_bf16_f32 v93, v86, v87
	v_lshl_add_u64 v[96:97], v[156:157], 1, v[96:97]
	v_cmp_gt_u64_e32 vcc, s[20:21], v[90:91]
	v_cvt_pk_bf16_f32 v94, v80, v81
	v_cvt_pk_bf16_f32 v95, v82, v83
	global_store_dwordx4 v[96:97], v[92:95], off sc0 sc1
	s_and_saveexec_b64 s[26:27], vcc
	s_xor_b64 s[26:27], exec, s[26:27]
	s_cbranch_execz .LBB0_420
	v_and_b32_e32 v91, 0x3fff, v90
	v_cmp_lt_u32_e32 vcc, s78, v91
	v_mov_b64_e32 v[92:93], 0
	s_and_saveexec_b64 s[28:29], vcc
	v_lshrrev_b32_e32 v90, 14, v90
	v_mul_u32_u24_e32 v90, 30, v90
	v_add3_u32 v144, v91, v90, s79
	v_lshlrev_b64 v[90:91], 11, v[144:145]
	v_lshl_add_u64 v[90:91], s[6:7], 0, v[90:91]
	v_lshl_add_u64 v[92:93], v[156:157], 2, v[90:91]
	s_or_b64 exec, exec, s[28:29]
	s_andn2_saveexec_b64 s[26:27], s[26:27]
	s_cbranch_execnz .LBB0_421

;     __device__ __forceinline__ void conv_piece(size_t row, int ch, f32x4 v0, f32x4 v1, const f32x4 g0, const f32x4 g1) const {
;     ...
;         if (row >= (size_t)NP) { const int r = (int)row - NP; dst = out + O_CVS + (size_t)((r >> 4) * 30 + 14 + (r & 15)) * DCONV + ch; }
;         else { const int t = (int)row & (SEQ - 1); if (t >= SEQ - 30) dst = out + O_CVP + (size_t)(((int)row >> 14) * 30 + (t - (SEQ - 30))) * DCONV + ch; }
;         if (dst) { *(f32x4*)dst = v0; *(f32x4*)(dst + 4) = v1; }
.LBB0_367:
	global_store_dwordx4 v[92:93], v[84:87], off sc0 sc1
	global_store_dwordx4 v[92:93], v[80:83], off offset:16 sc0 sc1

; #define LAS __attribute__((address_space(3)))
; __device__ __forceinline__ float sigmoidf_(float x) { return __builtin_amdgcn_rcpf(1.f + __builtin_amdgcn_exp2f(-1.4426950408889634f * x)); }
; #define EPI_FOR_ROWS for (int ai = 0; ai < 2; ++ai) _Pragma("unroll") for (int m = 0; m < 4; ++m)
; __device__ __forceinline__ u32x4 pack8(const f32x4 a, const f32x4 b) { u32x4 w; w.x = cvt_pk_bf16(a[0], a[1]); w.y = cvt_pk_bf16(a[2], a[3]); w.z = cvt_pk_bf16(b[0], b[1]); w.w = cvt_pk_bf16(b[2], b[3]); return w; }
;     __device__ __forceinline__ void conv_piece(size_t row, int ch, f32x4 v0, f32x4 v1, const f32x4 g0, const f32x4 g1) const {
; #pragma unroll
;         for (int e = 0; e < 4; ++e) { v0[e] *= sigmoidf_(g0[e]); v1[e] *= sigmoidf_(g1[e]); }
;         *(u32x4*)(Vb + row * DCONV + ch) = pack8(v0, v1);
;         float* dst = nullptr;
;         if (row >= (size_t)NP) { const int r = (int)row - NP; dst = out + O_CVS + (size_t)((r >> 4) * 30 + 14 + (r & 15)) * DCONV + ch; }
;         else { const int t = (int)row & (SEQ - 1); if (t >= SEQ - 30) dst = out + O_CVP + (size_t)(((int)row >> 14) * 30 + (t - (SEQ - 30))) * DCONV + ch; }
;         if (dst) { *(f32x4*)dst = v0; *(f32x4*)(dst + 4) = v1; }
;     }
;     __device__ __forceinline__ void small(size_t row, int col, const f32x4 v0, const f32x4 v1) const { *(u32x4*)(Ub + row * DSSM + col) = pack8(v0, v1); }
;     __device__ __forceinline__ void operator()(const f32x4 (&acc)[2][2][4][2], const Unit& u, int wr, int wc, int fr_, int fq_, LAS unsigned char*) const {
;         int fr = fr_, fq = fq_; asm volatile("" : "+v"(fr), "+v"(fq));
;         const int pn = u.aux;
; #pragma unroll
;         EPI_FOR_ROWS {
;             const int rl = ai * HALF + wr * 64 + m * 16 + fr; const size_t row = (size_t)u.row0 + rl;
;             if (pn < 2) {
; #pragma unroll
;                 for (int bj = 0; bj < 2; ++bj) *(u32x4*)(Ub + row * DSSM + pn * 256 + bj * HALF + wc * 32 + 8 * fq) = pack8(acc[ai][bj][m][0], acc[ai][bj][m][1]);
;             } else {
;                 conv_piece(row, (pn - 2) * 128 + wc * 32 + 8 * fq, acc[ai][0][m][0], acc[ai][0][m][1], acc[ai][1][m][0], acc[ai][1][m][1]);
.LBB0_369:
	s_and_b64 vcc, exec, s[26:27]
	s_cbranch_vccz .LBB0_371
	v_cvt_pk_bf16_f32 v76, v76, v77
	v_cvt_pk_bf16_f32 v77, v78, v79
	v_cvt_pk_bf16_f32 v78, v72, v73
	v_lshl_add_u64 v[72:73], s[60:61], 0, v[88:89]
	v_lshl_add_u64 v[72:73], s[62:63], 1, v[72:73]
	s_lshl_b32 s10, s71, 1
	v_lshl_add_u64 v[72:73], v[72:73], 0, s[10:11]
	v_lshl_add_u64 v[72:73], v[154:155], 1, v[72:73]
	v_cvt_pk_bf16_f32 v79, v74, v75
	global_store_dwordx4 v[72:73], v[76:79], off sc0 sc1
	v_cvt_pk_bf16_f32 v68, v68, v69
	v_cvt_pk_bf16_f32 v69, v70, v71
	v_cvt_pk_bf16_f32 v70, v64, v65
	v_cvt_pk_bf16_f32 v71, v66, v67
	global_store_dwordx4 v[72:73], v[68:71], off offset:256 sc0 sc1
.LBB0_371:
	v_add_u32_e32 v64, 0x80, v158
	v_ashrrev_i32_e32 v65, 31, v64
	v_lshl_add_u64 v[74:75], v[64:65], 0, s[16:17]
	s_mov_b64 s[26:27], -1
	s_and_b64 vcc, exec, s[4:5]
	v_lshlrev_b64 v[72:73], 10, v[74:75]
	s_cbranch_vccnz .LBB0_379
	v_mul_f32_e32 v65, 0xbfb8aa3b, v48
	v_mul_f32_e32 v66, 0xbfb8aa3b, v53
	v_exp_f32_e32 v65, v65
	v_exp_f32_e32 v67, v66
	v_mul_f32_e32 v66, 0xbfb8aa3b, v49
	v_exp_f32_e32 v68, v66
	v_add_f32_e32 v65, 1.0, v65
	v_rcp_f32_e32 v66, v65
	v_add_f32_e32 v65, 1.0, v67
	v_add_f32_e32 v67, 1.0, v68
	v_mul_f32_e32 v68, 0xbfb8aa3b, v54
	v_exp_f32_e32 v68, v68
	v_mul_f32_e32 v69, 0xbfb8aa3b, v50
	v_exp_f32_e32 v69, v69
	v_mul_f32_e32 v64, 0xbfb8aa3b, v52
	v_add_f32_e32 v68, 1.0, v68
	v_rcp_f32_e32 v70, v68
	v_add_f32_e32 v68, 1.0, v69
	v_mul_f32_e32 v69, 0xbfb8aa3b, v55
	v_exp_f32_e32 v69, v69
	v_mul_f32_e32 v71, 0xbfb8aa3b, v51
	v_exp_f32_e32 v64, v64
	v_exp_f32_e32 v77, v71
	v_rcp_f32_e32 v76, v68
	v_add_f32_e32 v68, 1.0, v69
	v_add_f32_e32 v64, 1.0, v64
	v_rcp_f32_e32 v71, v68
	v_add_f32_e32 v68, 1.0, v77
	v_rcp_f32_e32 v64, v64
	v_rcp_f32_e32 v65, v65
	v_rcp_f32_e32 v67, v67
	v_rcp_f32_e32 v77, v68
	v_lshl_add_u64 v[80:81], s[36:37], 0, v[72:73]
	v_pk_mul_f32 v[68:69], v[60:61], v[64:65]
	v_pk_mul_f32 v[64:65], v[56:57], v[66:67]
	v_pk_mul_f32 v[70:71], v[62:63], v[70:71]
	v_pk_mul_f32 v[66:67], v[58:59], v[76:77]
	v_cvt_pk_bf16_f32 v76, v68, v69
	v_cvt_pk_bf16_f32 v77, v70, v71
	v_lshl_add_u64 v[80:81], v[156:157], 1, v[80:81]
	v_cmp_gt_u64_e32 vcc, s[20:21], v[74:75]
	v_cvt_pk_bf16_f32 v78, v64, v65
	v_cvt_pk_bf16_f32 v79, v66, v67
	global_store_dwordx4 v[80:81], v[76:79], off sc0 sc1
	s_and_saveexec_b64 s[26:27], vcc
	s_xor_b64 s[26:27], exec, s[26:27]
	s_cbranch_execz .LBB0_422
	v_and_b32_e32 v75, 0x3fff, v74
	v_cmp_lt_u32_e32 vcc, s78, v75
	v_mov_b64_e32 v[76:77], 0
	s_and_saveexec_b64 s[28:29], vcc
	v_lshrrev_b32_e32 v74, 14, v74
	v_mul_u32_u24_e32 v74, 30, v74
	v_add3_u32 v144, v75, v74, s79
	v_lshlrev_b64 v[74:75], 11, v[144:145]
	v_lshl_add_u64 v[74:75], s[6:7], 0, v[74:75]
	v_lshl_add_u64 v[76:77], v[156:157], 2, v[74:75]
	s_or_b64 exec, exec, s[28:29]
	s_andn2_saveexec_b64 s[26:27], s[26:27]
	s_cbranch_execnz .LBB0_423

;     __device__ __forceinline__ void conv_piece(size_t row, int ch, f32x4 v0, f32x4 v1, const f32x4 g0, const f32x4 g1) const {
;     ...
;         if (row >= (size_t)NP) { const int r = (int)row - NP; dst = out + O_CVS + (size_t)((r >> 4) * 30 + 14 + (r & 15)) * DCONV + ch; }
;         else { const int t = (int)row & (SEQ - 1); if (t >= SEQ - 30) dst = out + O_CVP + (size_t)(((int)row >> 14) * 30 + (t - (SEQ - 30))) * DCONV + ch; }
;         if (dst) { *(f32x4*)dst = v0; *(f32x4*)(dst + 4) = v1; }
.LBB0_377:
	global_store_dwordx4 v[76:77], v[68:71], off sc0 sc1
	global_store_dwordx4 v[76:77], v[64:67], off offset:16 sc0 sc1

; #define LAS __attribute__((address_space(3)))
; __device__ __forceinline__ float sigmoidf_(float x) { return __builtin_amdgcn_rcpf(1.f + __builtin_amdgcn_exp2f(-1.4426950408889634f * x)); }
; #define EPI_FOR_ROWS for (int ai = 0; ai < 2; ++ai) _Pragma("unroll") for (int m = 0; m < 4; ++m)
; __device__ __forceinline__ u32x4 pack8(const f32x4 a, const f32x4 b) { u32x4 w; w.x = cvt_pk_bf16(a[0], a[1]); w.y = cvt_pk_bf16(a[2], a[3]); w.z = cvt_pk_bf16(b[0], b[1]); w.w = cvt_pk_bf16(b[2], b[3]); return w; }
;     __device__ __forceinline__ void conv_piece(size_t row, int ch, f32x4 v0, f32x4 v1, const f32x4 g0, const f32x4 g1) const {
; #pragma unroll
;         for (int e = 0; e < 4; ++e) { v0[e] *= sigmoidf_(g0[e]); v1[e] *= sigmoidf_(g1[e]); }
;         *(u32x4*)(Vb + row * DCONV + ch) = pack8(v0, v1);
;         float* dst = nullptr;
;         if (row >= (size_t)NP) { const int r = (int)row - NP; dst = out + O_CVS + (size_t)((r >> 4) * 30 + 14 + (r & 15)) * DCONV + ch; }
;         else { const int t = (int)row & (SEQ - 1); if (t >= SEQ - 30) dst = out + O_CVP + (size_t)(((int)row >> 14) * 30 + (t - (SEQ - 30))) * DCONV + ch; }
;         if (dst) { *(f32x4*)dst = v0; *(f32x4*)(dst + 4) = v1; }
;     }
;     __device__ __forceinline__ void small(size_t row, int col, const f32x4 v0, const f32x4 v1) const { *(u32x4*)(Ub + row * DSSM + col) = pack8(v0, v1); }
;     __device__ __forceinline__ void operator()(const f32x4 (&acc)[2][2][4][2], const Unit& u, int wr, int wc, int fr_, int fq_, LAS unsigned char*) const {
;         int fr = fr_, fq = fq_; asm volatile("" : "+v"(fr), "+v"(fq));
;         const int pn = u.aux;
; #pragma unroll
;         EPI_FOR_ROWS {
;             const int rl = ai * HALF + wr * 64 + m * 16 + fr; const size_t row = (size_t)u.row0 + rl;
;             if (pn < 2) {
; #pragma unroll
;                 for (int bj = 0; bj < 2; ++bj) *(u32x4*)(Ub + row * DSSM + pn * 256 + bj * HALF + wc * 32 + 8 * fq) = pack8(acc[ai][bj][m][0], acc[ai][bj][m][1]);
;             } else {
;                 conv_piece(row, (pn - 2) * 128 + wc * 32 + 8 * fq, acc[ai][0][m][0], acc[ai][0][m][1], acc[ai][1][m][0], acc[ai][1][m][1]);
.LBB0_379:
	s_and_b64 vcc, exec, s[26:27]
	s_cbranch_vccz .LBB0_381
	v_cvt_pk_bf16_f32 v60, v60, v61
	v_cvt_pk_bf16_f32 v61, v62, v63
	v_cvt_pk_bf16_f32 v62, v56, v57
	v_lshl_add_u64 v[56:57], s[60:61], 0, v[72:73]
	v_lshl_add_u64 v[56:57], s[62:63], 1, v[56:57]
	s_lshl_b32 s10, s71, 1
	v_lshl_add_u64 v[56:57], v[56:57], 0, s[10:11]
	v_lshl_add_u64 v[56:57], v[154:155], 1, v[56:57]
	v_cvt_pk_bf16_f32 v63, v58, v59
	global_store_dwordx4 v[56:57], v[60:63], off sc0 sc1
	v_cvt_pk_bf16_f32 v52, v52, v53
	v_cvt_pk_bf16_f32 v53, v54, v55
	v_cvt_pk_bf16_f32 v54, v48, v49
	v_cvt_pk_bf16_f32 v55, v50, v51
	global_store_dwordx4 v[56:57], v[52:55], off offset:256 sc0 sc1
.LBB0_381:
	v_add_u32_e32 v48, 0x90, v158
	v_ashrrev_i32_e32 v49, 31, v48
	v_lshl_add_u64 v[58:59], v[48:49], 0, s[16:17]
	s_mov_b64 s[26:27], -1
	s_and_b64 vcc, exec, s[4:5]
	v_lshlrev_b64 v[56:57], 10, v[58:59]
	s_cbranch_vccnz .LBB0_389
	v_mul_f32_e32 v49, 0xbfb8aa3b, v32
	v_mul_f32_e32 v50, 0xbfb8aa3b, v37
	v_exp_f32_e32 v49, v49
	v_exp_f32_e32 v51, v50
	v_mul_f32_e32 v50, 0xbfb8aa3b, v33
	v_exp_f32_e32 v52, v50
	v_add_f32_e32 v49, 1.0, v49
	v_rcp_f32_e32 v50, v49
	v_add_f32_e32 v49, 1.0, v51
	v_add_f32_e32 v51, 1.0, v52
	v_mul_f32_e32 v52, 0xbfb8aa3b, v38
	v_exp_f32_e32 v52, v52
	v_mul_f32_e32 v53, 0xbfb8aa3b, v34
	v_exp_f32_e32 v53, v53
	v_mul_f32_e32 v48, 0xbfb8aa3b, v36
	v_add_f32_e32 v52, 1.0, v52
	v_rcp_f32_e32 v54, v52
	v_add_f32_e32 v52, 1.0, v53
	v_mul_f32_e32 v53, 0xbfb8aa3b, v39
	v_exp_f32_e32 v53, v53
	v_mul_f32_e32 v55, 0xbfb8aa3b, v35
	v_exp_f32_e32 v48, v48
	v_exp_f32_e32 v61, v55
	v_rcp_f32_e32 v60, v52
	v_add_f32_e32 v52, 1.0, v53
	v_add_f32_e32 v48, 1.0, v48
	v_rcp_f32_e32 v55, v52
	v_add_f32_e32 v52, 1.0, v61
	v_rcp_f32_e32 v48, v48
	v_rcp_f32_e32 v49, v49
	v_rcp_f32_e32 v51, v51
	v_rcp_f32_e32 v61, v52
	v_lshl_add_u64 v[64:65], s[36:37], 0, v[56:57]
	v_pk_mul_f32 v[52:53], v[44:45], v[48:49]
	v_pk_mul_f32 v[48:49], v[40:41], v[50:51]
	v_pk_mul_f32 v[54:55], v[46:47], v[54:55]
	v_pk_mul_f32 v[50:51], v[42:43], v[60:61]
	v_cvt_pk_bf16_f32 v60, v52, v53
	v_cvt_pk_bf16_f32 v61, v54, v55
	v_lshl_add_u64 v[64:65], v[156:157], 1, v[64:65]
	v_cmp_gt_u64_e32 vcc, s[20:21], v[58:59]
	v_cvt_pk_bf16_f32 v62, v48, v49
	v_cvt_pk_bf16_f32 v63, v50, v51
	global_store_dwordx4 v[64:65], v[60:63], off sc0 sc1
	s_and_saveexec_b64 s[26:27], vcc
	s_xor_b64 s[26:27], exec, s[26:27]
	s_cbranch_execz .LBB0_424
	v_and_b32_e32 v59, 0x3fff, v58
	v_cmp_lt_u32_e32 vcc, s78, v59
	v_mov_b64_e32 v[60:61], 0
	s_and_saveexec_b64 s[28:29], vcc
	v_lshrrev_b32_e32 v58, 14, v58
	v_mul_u32_u24_e32 v58, 30, v58
	v_add3_u32 v144, v59, v58, s79
	v_lshlrev_b64 v[58:59], 11, v[144:145]
	v_lshl_add_u64 v[58:59], s[6:7], 0, v[58:59]
	v_lshl_add_u64 v[60:61], v[156:157], 2, v[58:59]
	s_or_b64 exec, exec, s[28:29]
	s_andn2_saveexec_b64 s[26:27], s[26:27]
	s_cbranch_execnz .LBB0_425

;     __device__ __forceinline__ void conv_piece(size_t row, int ch, f32x4 v0, f32x4 v1, const f32x4 g0, const f32x4 g1) const {
;     ...
;         if (row >= (size_t)NP) { const int r = (int)row - NP; dst = out + O_CVS + (size_t)((r >> 4) * 30 + 14 + (r & 15)) * DCONV + ch; }
;         else { const int t = (int)row & (SEQ - 1); if (t >= SEQ - 30) dst = out + O_CVP + (size_t)(((int)row >> 14) * 30 + (t - (SEQ - 30))) * DCONV + ch; }
;         if (dst) { *(f32x4*)dst = v0; *(f32x4*)(dst + 4) = v1; }
.LBB0_387:
	global_store_dwordx4 v[60:61], v[52:55], off sc0 sc1
	global_store_dwordx4 v[60:61], v[48:51], off offset:16 sc0 sc1

; #define LAS __attribute__((address_space(3)))
; __device__ __forceinline__ float sigmoidf_(float x) { return __builtin_amdgcn_rcpf(1.f + __builtin_amdgcn_exp2f(-1.4426950408889634f * x)); }
; #define EPI_FOR_ROWS for (int ai = 0; ai < 2; ++ai) _Pragma("unroll") for (int m = 0; m < 4; ++m)
; __device__ __forceinline__ u32x4 pack8(const f32x4 a, const f32x4 b) { u32x4 w; w.x = cvt_pk_bf16(a[0], a[1]); w.y = cvt_pk_bf16(a[2], a[3]); w.z = cvt_pk_bf16(b[0], b[1]); w.w = cvt_pk_bf16(b[2], b[3]); return w; }
;     __device__ __forceinline__ void conv_piece(size_t row, int ch, f32x4 v0, f32x4 v1, const f32x4 g0, const f32x4 g1) const {
; #pragma unroll
;         for (int e = 0; e < 4; ++e) { v0[e] *= sigmoidf_(g0[e]); v1[e] *= sigmoidf_(g1[e]); }
;         *(u32x4*)(Vb + row * DCONV + ch) = pack8(v0, v1);
;         float* dst = nullptr;
;         if (row >= (size_t)NP) { const int r = (int)row - NP; dst = out + O_CVS + (size_t)((r >> 4) * 30 + 14 + (r & 15)) * DCONV + ch; }
;         else { const int t = (int)row & (SEQ - 1); if (t >= SEQ - 30) dst = out + O_CVP + (size_t)(((int)row >> 14) * 30 + (t - (SEQ - 30))) * DCONV + ch; }
;         if (dst) { *(f32x4*)dst = v0; *(f32x4*)(dst + 4) = v1; }
;     }
;     __device__ __forceinline__ void small(size_t row, int col, const f32x4 v0, const f32x4 v1) const { *(u32x4*)(Ub + row * DSSM + col) = pack8(v0, v1); }
;     __device__ __forceinline__ void operator()(const f32x4 (&acc)[2][2][4][2], const Unit& u, int wr, int wc, int fr_, int fq_, LAS unsigned char*) const {
;         int fr = fr_, fq = fq_; asm volatile("" : "+v"(fr), "+v"(fq));
;         const int pn = u.aux;
; #pragma unroll
;         EPI_FOR_ROWS {
;             const int rl = ai * HALF + wr * 64 + m * 16 + fr; const size_t row = (size_t)u.row0 + rl;
;             if (pn < 2) {
; #pragma unroll
;                 for (int bj = 0; bj < 2; ++bj) *(u32x4*)(Ub + row * DSSM + pn * 256 + bj * HALF + wc * 32 + 8 * fq) = pack8(acc[ai][bj][m][0], acc[ai][bj][m][1]);
;             } else {
;                 conv_piece(row, (pn - 2) * 128 + wc * 32 + 8 * fq, acc[ai][0][m][0], acc[ai][0][m][1], acc[ai][1][m][0], acc[ai][1][m][1]);
.LBB0_389:
	s_and_b64 vcc, exec, s[26:27]
	s_cbranch_vccz .LBB0_391
	v_cvt_pk_bf16_f32 v44, v44, v45
	v_cvt_pk_bf16_f32 v45, v46, v47
	v_cvt_pk_bf16_f32 v46, v40, v41
	v_lshl_add_u64 v[40:41], s[60:61], 0, v[56:57]
	v_lshl_add_u64 v[40:41], s[62:63], 1, v[40:41]
	s_lshl_b32 s10, s71, 1
	v_lshl_add_u64 v[40:41], v[40:41], 0, s[10:11]
	v_lshl_add_u64 v[40:41], v[154:155], 1, v[40:41]
	v_cvt_pk_bf16_f32 v47, v42, v43
	global_store_dwordx4 v[40:41], v[44:47], off sc0 sc1
	v_cvt_pk_bf16_f32 v36, v36, v37
	v_cvt_pk_bf16_f32 v37, v38, v39
	v_cvt_pk_bf16_f32 v38, v32, v33
	v_cvt_pk_bf16_f32 v39, v34, v35
	global_store_dwordx4 v[40:41], v[36:39], off offset:256 sc0 sc1
.LBB0_391:
	v_add_u32_e32 v32, 0xa0, v158
	v_ashrrev_i32_e32 v33, 31, v32
	v_lshl_add_u64 v[42:43], v[32:33], 0, s[16:17]
	s_mov_b64 s[26:27], -1
	s_and_b64 vcc, exec, s[4:5]
	v_lshlrev_b64 v[40:41], 10, v[42:43]
	s_cbranch_vccnz .LBB0_399
	v_mul_f32_e32 v33, 0xbfb8aa3b, v16
	v_mul_f32_e32 v34, 0xbfb8aa3b, v21
	v_exp_f32_e32 v33, v33
	v_exp_f32_e32 v35, v34
	v_mul_f32_e32 v34, 0xbfb8aa3b, v17
	v_exp_f32_e32 v36, v34
	v_add_f32_e32 v33, 1.0, v33
	v_rcp_f32_e32 v34, v33
	v_add_f32_e32 v33, 1.0, v35
	v_add_f32_e32 v35, 1.0, v36
	v_mul_f32_e32 v36, 0xbfb8aa3b, v22
	v_exp_f32_e32 v36, v36
	v_mul_f32_e32 v37, 0xbfb8aa3b, v18
	v_exp_f32_e32 v37, v37
	v_mul_f32_e32 v32, 0xbfb8aa3b, v20
	v_add_f32_e32 v36, 1.0, v36
	v_rcp_f32_e32 v38, v36
	v_add_f32_e32 v36, 1.0, v37
	v_mul_f32_e32 v37, 0xbfb8aa3b, v23
	v_exp_f32_e32 v37, v37
	v_mul_f32_e32 v39, 0xbfb8aa3b, v19
	v_exp_f32_e32 v32, v32
	v_exp_f32_e32 v45, v39
	v_rcp_f32_e32 v44, v36
	v_add_f32_e32 v36, 1.0, v37
	v_add_f32_e32 v32, 1.0, v32
	v_rcp_f32_e32 v39, v36
	v_add_f32_e32 v36, 1.0, v45
	v_rcp_f32_e32 v32, v32
	v_rcp_f32_e32 v33, v33
	v_rcp_f32_e32 v35, v35
	v_rcp_f32_e32 v45, v36
	v_lshl_add_u64 v[48:49], s[36:37], 0, v[40:41]
	v_pk_mul_f32 v[36:37], v[28:29], v[32:33]
	v_pk_mul_f32 v[32:33], v[24:25], v[34:35]
	v_pk_mul_f32 v[38:39], v[30:31], v[38:39]
	v_pk_mul_f32 v[34:35], v[26:27], v[44:45]
	v_cvt_pk_bf16_f32 v44, v36, v37
	v_cvt_pk_bf16_f32 v45, v38, v39
	v_lshl_add_u64 v[48:49], v[156:157], 1, v[48:49]
	v_cmp_gt_u64_e32 vcc, s[20:21], v[42:43]
	v_cvt_pk_bf16_f32 v46, v32, v33
	v_cvt_pk_bf16_f32 v47, v34, v35
	global_store_dwordx4 v[48:49], v[44:47], off sc0 sc1
	s_and_saveexec_b64 s[26:27], vcc
	s_xor_b64 s[26:27], exec, s[26:27]
	s_cbranch_execz .LBB0_426
	v_and_b32_e32 v43, 0x3fff, v42
	v_cmp_lt_u32_e32 vcc, s78, v43
	v_mov_b64_e32 v[44:45], 0
	s_and_saveexec_b64 s[28:29], vcc
	v_lshrrev_b32_e32 v42, 14, v42
	v_mul_u32_u24_e32 v42, 30, v42
	v_add3_u32 v144, v43, v42, s79
	v_lshlrev_b64 v[42:43], 11, v[144:145]
	v_lshl_add_u64 v[42:43], s[6:7], 0, v[42:43]
	v_lshl_add_u64 v[44:45], v[156:157], 2, v[42:43]
	s_or_b64 exec, exec, s[28:29]
	s_andn2_saveexec_b64 s[26:27], s[26:27]
	s_cbranch_execnz .LBB0_427

;     __device__ __forceinline__ void conv_piece(size_t row, int ch, f32x4 v0, f32x4 v1, const f32x4 g0, const f32x4 g1) const {
;     ...
;         if (row >= (size_t)NP) { const int r = (int)row - NP; dst = out + O_CVS + (size_t)((r >> 4) * 30 + 14 + (r & 15)) * DCONV + ch; }
;         else { const int t = (int)row & (SEQ - 1); if (t >= SEQ - 30) dst = out + O_CVP + (size_t)(((int)row >> 14) * 30 + (t - (SEQ - 30))) * DCONV + ch; }
;         if (dst) { *(f32x4*)dst = v0; *(f32x4*)(dst + 4) = v1; }
.LBB0_397:
	global_store_dwordx4 v[44:45], v[36:39], off sc0 sc1
	global_store_dwordx4 v[44:45], v[32:35], off offset:16 sc0 sc1

; #define LAS __attribute__((address_space(3)))
; __device__ __forceinline__ float sigmoidf_(float x) { return __builtin_amdgcn_rcpf(1.f + __builtin_amdgcn_exp2f(-1.4426950408889634f * x)); }
; #define EPI_FOR_ROWS for (int ai = 0; ai < 2; ++ai) _Pragma("unroll") for (int m = 0; m < 4; ++m)
; __device__ __forceinline__ u32x4 pack8(const f32x4 a, const f32x4 b) { u32x4 w; w.x = cvt_pk_bf16(a[0], a[1]); w.y = cvt_pk_bf16(a[2], a[3]); w.z = cvt_pk_bf16(b[0], b[1]); w.w = cvt_pk_bf16(b[2], b[3]); return w; }
;     __device__ __forceinline__ void conv_piece(size_t row, int ch, f32x4 v0, f32x4 v1, const f32x4 g0, const f32x4 g1) const {
; #pragma unroll
;         for (int e = 0; e < 4; ++e) { v0[e] *= sigmoidf_(g0[e]); v1[e] *= sigmoidf_(g1[e]); }
;         *(u32x4*)(Vb + row * DCONV + ch) = pack8(v0, v1);
;         float* dst = nullptr;
;         if (row >= (size_t)NP) { const int r = (int)row - NP; dst = out + O_CVS + (size_t)((r >> 4) * 30 + 14 + (r & 15)) * DCONV + ch; }
;         else { const int t = (int)row & (SEQ - 1); if (t >= SEQ - 30) dst = out + O_CVP + (size_t)(((int)row >> 14) * 30 + (t - (SEQ - 30))) * DCONV + ch; }
;         if (dst) { *(f32x4*)dst = v0; *(f32x4*)(dst + 4) = v1; }
;     }
;     __device__ __forceinline__ void small(size_t row, int col, const f32x4 v0, const f32x4 v1) const { *(u32x4*)(Ub + row * DSSM + col) = pack8(v0, v1); }
;     __device__ __forceinline__ void operator()(const f32x4 (&acc)[2][2][4][2], const Unit& u, int wr, int wc, int fr_, int fq_, LAS unsigned char*) const {
;         int fr = fr_, fq = fq_; asm volatile("" : "+v"(fr), "+v"(fq));
;         const int pn = u.aux;
; #pragma unroll
;         EPI_FOR_ROWS {
;             const int rl = ai * HALF + wr * 64 + m * 16 + fr; const size_t row = (size_t)u.row0 + rl;
;             if (pn < 2) {
; #pragma unroll
;                 for (int bj = 0; bj < 2; ++bj) *(u32x4*)(Ub + row * DSSM + pn * 256 + bj * HALF + wc * 32 + 8 * fq) = pack8(acc[ai][bj][m][0], acc[ai][bj][m][1]);
;             } else {
;                 conv_piece(row, (pn - 2) * 128 + wc * 32 + 8 * fq, acc[ai][0][m][0], acc[ai][0][m][1], acc[ai][1][m][0], acc[ai][1][m][1]);
.LBB0_399:
	s_and_b64 vcc, exec, s[26:27]
	s_cbranch_vccz .LBB0_401
	v_cvt_pk_bf16_f32 v28, v28, v29
	v_cvt_pk_bf16_f32 v29, v30, v31
	v_cvt_pk_bf16_f32 v30, v24, v25
	v_lshl_add_u64 v[24:25], s[60:61], 0, v[40:41]
	v_lshl_add_u64 v[24:25], s[62:63], 1, v[24:25]
	s_lshl_b32 s10, s71, 1
	v_lshl_add_u64 v[24:25], v[24:25], 0, s[10:11]
	v_lshl_add_u64 v[24:25], v[154:155], 1, v[24:25]
	v_cvt_pk_bf16_f32 v31, v26, v27
	global_store_dwordx4 v[24:25], v[28:31], off sc0 sc1
	v_cvt_pk_bf16_f32 v20, v20, v21
	v_cvt_pk_bf16_f32 v21, v22, v23
	v_cvt_pk_bf16_f32 v22, v16, v17
	v_cvt_pk_bf16_f32 v23, v18, v19
	global_store_dwordx4 v[24:25], v[20:23], off offset:256 sc0 sc1
.LBB0_401:
	v_add_u32_e32 v16, 0xb0, v158
	v_ashrrev_i32_e32 v17, 31, v16
	v_lshl_add_u64 v[26:27], v[16:17], 0, s[16:17]
	s_mov_b64 s[16:17], -1
	s_and_b64 vcc, exec, s[4:5]
	v_lshlrev_b64 v[24:25], 10, v[26:27]
	s_cbranch_vccnz .LBB0_410
	v_mul_f32_e32 v17, 0xbfb8aa3b, v0
	v_mul_f32_e32 v18, 0xbfb8aa3b, v5
	v_exp_f32_e32 v17, v17
	v_exp_f32_e32 v19, v18
	v_mul_f32_e32 v18, 0xbfb8aa3b, v1
	v_exp_f32_e32 v20, v18
	v_add_f32_e32 v17, 1.0, v17
	v_rcp_f32_e32 v18, v17
	v_add_f32_e32 v17, 1.0, v19
	v_add_f32_e32 v19, 1.0, v20
	v_mul_f32_e32 v20, 0xbfb8aa3b, v6
	v_exp_f32_e32 v20, v20
	v_mul_f32_e32 v21, 0xbfb8aa3b, v2
	v_exp_f32_e32 v21, v21
	v_mul_f32_e32 v16, 0xbfb8aa3b, v4
	v_add_f32_e32 v20, 1.0, v20
	v_rcp_f32_e32 v22, v20
	v_add_f32_e32 v20, 1.0, v21
	v_mul_f32_e32 v21, 0xbfb8aa3b, v7
	v_exp_f32_e32 v21, v21
	v_mul_f32_e32 v23, 0xbfb8aa3b, v3
	v_exp_f32_e32 v16, v16
	v_exp_f32_e32 v29, v23
	v_rcp_f32_e32 v28, v20
	v_add_f32_e32 v20, 1.0, v21
	v_add_f32_e32 v16, 1.0, v16
	v_rcp_f32_e32 v23, v20
	v_add_f32_e32 v20, 1.0, v29
	v_rcp_f32_e32 v16, v16
	v_rcp_f32_e32 v17, v17
	v_rcp_f32_e32 v19, v19
	v_rcp_f32_e32 v29, v20
	v_lshl_add_u64 v[32:33], s[36:37], 0, v[24:25]
	v_pk_mul_f32 v[20:21], v[12:13], v[16:17]
	v_pk_mul_f32 v[16:17], v[8:9], v[18:19]
	v_pk_mul_f32 v[22:23], v[14:15], v[22:23]
	v_pk_mul_f32 v[18:19], v[10:11], v[28:29]
	v_cvt_pk_bf16_f32 v28, v20, v21
	v_cvt_pk_bf16_f32 v29, v22, v23
	v_lshl_add_u64 v[32:33], v[156:157], 1, v[32:33]
	v_cmp_gt_u64_e32 vcc, s[20:21], v[26:27]
	v_cvt_pk_bf16_f32 v30, v16, v17
	v_cvt_pk_bf16_f32 v31, v18, v19
	global_store_dwordx4 v[32:33], v[28:31], off sc0 sc1
	s_and_saveexec_b64 s[4:5], vcc
	s_xor_b64 s[4:5], exec, s[4:5]
	s_cbranch_execz .LBB0_428
	v_and_b32_e32 v27, 0x3fff, v26
	v_cmp_lt_u32_e32 vcc, s78, v27
	v_mov_b64_e32 v[28:29], 0
	s_and_saveexec_b64 s[16:17], vcc
	v_lshrrev_b32_e32 v26, 14, v26
	v_mul_u32_u24_e32 v26, 30, v26
	v_add3_u32 v144, v27, v26, s79
	v_lshlrev_b64 v[26:27], 11, v[144:145]
	v_lshl_add_u64 v[26:27], s[6:7], 0, v[26:27]
	v_lshl_add_u64 v[28:29], v[156:157], 2, v[26:27]
	s_or_b64 exec, exec, s[16:17]
	s_andn2_saveexec_b64 s[4:5], s[4:5]
	s_cbranch_execnz .LBB0_429

;     __device__ __forceinline__ void conv_piece(size_t row, int ch, f32x4 v0, f32x4 v1, const f32x4 g0, const f32x4 g1) const {
;     ...
;         if (row >= (size_t)NP) { const int r = (int)row - NP; dst = out + O_CVS + (size_t)((r >> 4) * 30 + 14 + (r & 15)) * DCONV + ch; }
;         else { const int t = (int)row & (SEQ - 1); if (t >= SEQ - 30) dst = out + O_CVP + (size_t)(((int)row >> 14) * 30 + (t - (SEQ - 30))) * DCONV + ch; }
;         if (dst) { *(f32x4*)dst = v0; *(f32x4*)(dst + 4) = v1; }
.LBB0_407:
	global_store_dwordx4 v[28:29], v[20:23], off sc0 sc1
	global_store_dwordx4 v[28:29], v[16:19], off offset:16 sc0 sc1

; __device__ __forceinline__ u32x4 pack8(const f32x4 a, const f32x4 b) { u32x4 w; w.x = cvt_pk_bf16(a[0], a[1]); w.y = cvt_pk_bf16(a[2], a[3]); w.z = cvt_pk_bf16(b[0], b[1]); w.w = cvt_pk_bf16(b[2], b[3]); return w; }
;     __device__ __forceinline__ void operator()(const f32x4 (&acc)[2][2][4][2], const Unit& u, int wr, int wc, int fr_, int fq_, LAS unsigned char*) const {
;     ...
;             if (pn < 2) {
; #pragma unroll
;                 for (int bj = 0; bj < 2; ++bj) *(u32x4*)(Ub + row * DSSM + pn * 256 + bj * HALF + wc * 32 + 8 * fq) = pack8(acc[ai][bj][m][0], acc[ai][bj][m][1]);
.LBB0_410:
	s_and_b64 vcc, exec, s[16:17]
	s_cbranch_vccz .LBB0_409
	v_cvt_pk_bf16_f32 v12, v12, v13
	v_cvt_pk_bf16_f32 v13, v14, v15
	v_cvt_pk_bf16_f32 v14, v8, v9
	v_lshl_add_u64 v[8:9], s[60:61], 0, v[24:25]
	v_lshl_add_u64 v[8:9], s[62:63], 1, v[8:9]
	s_lshl_b32 s10, s71, 1
	v_lshl_add_u64 v[8:9], v[8:9], 0, s[10:11]
	v_lshl_add_u64 v[8:9], v[154:155], 1, v[8:9]
	v_cvt_pk_bf16_f32 v15, v10, v11
	global_store_dwordx4 v[8:9], v[12:15], off sc0 sc1
	v_cvt_pk_bf16_f32 v4, v4, v5
	v_cvt_pk_bf16_f32 v5, v6, v7
	v_cvt_pk_bf16_f32 v6, v0, v1
	v_cvt_pk_bf16_f32 v7, v2, v3
	global_store_dwordx4 v[8:9], v[4:7], off offset:256 sc0 sc1
	s_andn2_b64 vcc, exec, s[0:1]
	s_mov_b64 s[0:1], -1
	s_cbranch_vccnz .LBB0_324
